# GLU GEMM epilogue: the 8 bf16 mix loads of each 32-row group issued together into dead K-loop fragment registers (was one load per wait), on top of v046
# baseline (speedup 1.0000x reference)
; DI uint2 pk4(float a, float b, float c, float d) { uint2 r; r.x = pk2(a, b); r.y = pk2(c, d); return r; }
; DI float bflo(unsigned v) { return __uint_as_float(v << 16); }
; DI float bfhi(unsigned v) { return __uint_as_float(v & 0xffff0000u); }
; DI float sigmoidf_(float x) { return __builtin_amdgcn_rcpf(1.f + __builtin_amdgcn_exp2f(-LOG2E * x)); }
;   DI u16* r1() const { return (u16*)(ws + O_R1); }
;   DI u16* ysact() const { return (u16*)(ws + O_YSACT); }
;   DI void operator()(f32x16 (&acc)[2][4], int wm, int wn, int lane) const {
;     ...
;     for (int mt = 0; mt < 4; ++mt) {
;       const int tok = m0 + wm * 128 + mt * 32 + r32;
; #pragma unroll
;       for (int nt = 0; nt < 2; ++nt) {
;         uint2 pk[4];
; #pragma unroll
;         for (int q4 = 0; q4 < 4; ++q4) {
;           const int n = n0 + wn * 64 + nt * 32 + q4 * 8 + hh * 4;
;           const float4 bb = *(const float4*)(gb + n);
;           const uint2 ys = *(const uint2*)(c.ysact() + (size_t)tok * 256 + n);
;           pk[q4] = pk4(bflo(ys.x) * sigmoidf_(acc[nt][mt][q4 * 4 + 0] + bb.x), bfhi(ys.x) * sigmoidf_(acc[nt][mt][q4 * 4 + 1] + bb.y),
;                        bflo(ys.y) * sigmoidf_(acc[nt][mt][q4 * 4 + 2] + bb.z), bfhi(ys.y) * sigmoidf_(acc[nt][mt][q4 * 4 + 3] + bb.w));
;         }
;         u16* d_ = c.r1() + (size_t)tok * 1024 + 768 + n0 + wn * 64 + nt * 32 + hh * 16;
;         *(uint4*)d_ = make_uint4(pk[0].x, pk[0].y, pk[1].x, pk[1].y);
;         *(uint4*)(d_ + 8) = make_uint4(pk[2].x, pk[2].y, pk[3].x, pk[3].y);
;       }
.LBB0_345:
	global_load_dwordx4 v[134:137], v[174:175], off
	s_mul_hi_u32 s2, s13, 0xaaaaaaab
	s_lshr_b32 s2, s2, 4
	s_mul_i32 s2, s2, 24
	s_sub_i32 s2, s13, s2
	v_readlane_b32 s8, v251, 9
	s_add_i32 s2, s2, s8
	v_lshl_or_b32 v132, s2, 8, v215
	v_lshlrev_b32_e32 v128, 9, v132
	v_mov_b32_e32 v129, v165
	v_lshl_add_u64 v[128:129], v[176:177], 0, v[128:129]
	global_load_dwordx2 v[216:217], v[128:129], off
	global_load_dwordx2 v[218:219], v[128:129], off offset:16
	global_load_dwordx2 v[220:221], v[128:129], off offset:32
	global_load_dwordx2 v[222:223], v[128:129], off offset:48
	global_load_dwordx2 v[142:143], v[128:129], off offset:64
	global_load_dwordx2 v[144:145], v[128:129], off offset:80
	global_load_dwordx2 v[146:147], v[128:129], off offset:96
	global_load_dwordx2 v[148:149], v[128:129], off offset:112
	v_readlane_b32 s16, v253, 9
	v_lshlrev_b32_e32 v130, 11, v132
	v_mov_b32_e32 v131, v165
	v_readlane_b32 s22, v253, 15
	v_readlane_b32 s23, v253, 16
	s_mov_b32 s3, s43
	s_lshl_b32 s2, s28, 1
	v_mov_b32_e32 v189, v165
	s_mov_b32 s6, 0x3418000
	s_mov_b64 s[14:15], 0x3418600
	v_readlane_b32 s17, v253, 10
	s_mov_b64 s[16:17], 0x3418640
	s_mov_b32 s13, s12
	v_readlane_b32 s18, v253, 11
	v_readlane_b32 s19, v253, 12
	v_readlane_b32 s20, v253, 13
	v_readlane_b32 s21, v253, 14
	s_waitcnt vmcnt(0)
	v_mov_b32_e32 v138, v216
	v_mov_b32_e32 v139, v217
	v_add_f32_e32 v112, v112, v134
	v_add_f32_e32 v113, v113, v135
	v_add_f32_e32 v114, v114, v136
	v_add_f32_e32 v115, v115, v137
	v_mul_f32_e32 v112, 0xbfb8aa3b, v112
	v_mul_f32_e32 v113, 0xbfb8aa3b, v113
	v_mul_f32_e32 v114, 0xbfb8aa3b, v114
	v_mul_f32_e32 v115, 0xbfb8aa3b, v115
	v_exp_f32_e32 v112, v112
	v_exp_f32_e32 v113, v113
	v_exp_f32_e32 v114, v114
	v_exp_f32_e32 v115, v115
	v_add_f32_e32 v112, 1.0, v112
	v_add_f32_e32 v113, 1.0, v113
	v_add_f32_e32 v114, 1.0, v114
	v_add_f32_e32 v115, 1.0, v115
	v_rcp_f32_e32 v112, v112
	v_rcp_f32_e32 v113, v113
	v_rcp_f32_e32 v114, v114
	v_rcp_f32_e32 v115, v115
	v_lshlrev_b32_e32 v140, 16, v138
	v_and_b32_e32 v141, 0xffff0000, v138
	v_lshlrev_b32_e32 v134, 16, v139
	v_and_b32_e32 v135, 0xffff0000, v139
	v_pk_mul_f32 v[112:113], v[112:113], v[140:141]
	v_pk_mul_f32 v[114:115], v[114:115], v[134:135]
	v_cvt_pk_bf16_f32 v112, v112, v113
	v_cvt_pk_bf16_f32 v113, v114, v115
	global_load_dwordx4 v[134:137], v[174:175], off offset:32
	s_waitcnt vmcnt(0)
	v_add_f32_e32 v116, v116, v134
	s_waitcnt vmcnt(0)
	v_mov_b32_e32 v114, v218
	v_mov_b32_e32 v115, v219
	v_lshlrev_b32_e32 v138, 16, v114
	v_and_b32_e32 v139, 0xffff0000, v114
	v_add_f32_e32 v114, v117, v135
	v_add_f32_e32 v118, v118, v136
	v_add_f32_e32 v119, v119, v137
	v_mul_f32_e32 v116, 0xbfb8aa3b, v116
	v_mul_f32_e32 v114, 0xbfb8aa3b, v114
	v_mul_f32_e32 v118, 0xbfb8aa3b, v118
	v_mul_f32_e32 v119, 0xbfb8aa3b, v119
	v_exp_f32_e32 v116, v116
	v_exp_f32_e32 v114, v114
	v_exp_f32_e32 v118, v118
	v_exp_f32_e32 v119, v119
	v_add_f32_e32 v116, 1.0, v116
	v_add_f32_e32 v114, 1.0, v114
	v_add_f32_e32 v118, 1.0, v118
	v_add_f32_e32 v119, 1.0, v119
	v_rcp_f32_e32 v116, v116
	v_rcp_f32_e32 v117, v114
	v_rcp_f32_e32 v118, v118
	v_rcp_f32_e32 v119, v119
	v_lshlrev_b32_e32 v114, 16, v115
	v_and_b32_e32 v115, 0xffff0000, v115
	v_pk_mul_f32 v[116:117], v[116:117], v[138:139]
	v_pk_mul_f32 v[118:119], v[118:119], v[114:115]
	v_cvt_pk_bf16_f32 v114, v116, v117
	v_cvt_pk_bf16_f32 v115, v118, v119
	global_load_dwordx4 v[116:119], v[174:175], off offset:64
	s_waitcnt vmcnt(0)
	v_add_f32_e32 v116, v120, v116
	v_add_f32_e32 v117, v121, v117
	v_add_f32_e32 v118, v122, v118
	v_add_f32_e32 v119, v123, v119
	v_mul_f32_e32 v116, 0xbfb8aa3b, v116
	v_mul_f32_e32 v117, 0xbfb8aa3b, v117
	v_mul_f32_e32 v118, 0xbfb8aa3b, v118
	v_mul_f32_e32 v119, 0xbfb8aa3b, v119
	v_exp_f32_e32 v116, v116
	v_exp_f32_e32 v117, v117
	v_exp_f32_e32 v118, v118
	v_exp_f32_e32 v119, v119
	v_add_f32_e32 v116, 1.0, v116
	v_add_f32_e32 v117, 1.0, v117
	v_add_f32_e32 v118, 1.0, v118
	v_add_f32_e32 v119, 1.0, v119
	v_rcp_f32_e32 v116, v116
	v_rcp_f32_e32 v117, v117
	v_rcp_f32_e32 v118, v118
	v_rcp_f32_e32 v119, v119
	s_waitcnt vmcnt(0)
	v_mov_b32_e32 v134, v220
	v_mov_b32_e32 v135, v221
	v_lshlrev_b32_e32 v136, 16, v134
	v_and_b32_e32 v137, 0xffff0000, v134
	v_lshlrev_b32_e32 v120, 16, v135
	v_and_b32_e32 v121, 0xffff0000, v135
	v_pk_mul_f32 v[116:117], v[116:117], v[136:137]
	v_pk_mul_f32 v[118:119], v[118:119], v[120:121]
	v_cvt_pk_bf16_f32 v116, v116, v117
	v_cvt_pk_bf16_f32 v117, v118, v119
	global_load_dwordx4 v[118:121], v[174:175], off offset:96
	s_waitcnt vmcnt(0)
	v_add_f32_e32 v118, v124, v118
	v_add_f32_e32 v119, v125, v119
	v_add_f32_e32 v120, v126, v120
	v_add_f32_e32 v121, v127, v121
	v_mul_f32_e32 v118, 0xbfb8aa3b, v118
	v_mul_f32_e32 v119, 0xbfb8aa3b, v119
	v_mul_f32_e32 v120, 0xbfb8aa3b, v120
	v_mul_f32_e32 v121, 0xbfb8aa3b, v121
	v_exp_f32_e32 v118, v118
	v_exp_f32_e32 v119, v119
	v_exp_f32_e32 v120, v120
	v_exp_f32_e32 v121, v121
	v_add_f32_e32 v118, 1.0, v118
	v_add_f32_e32 v119, 1.0, v119
	v_add_f32_e32 v120, 1.0, v120
	v_add_f32_e32 v121, 1.0, v121
	v_rcp_f32_e32 v118, v118
	v_rcp_f32_e32 v119, v119
	v_rcp_f32_e32 v120, v120
	v_rcp_f32_e32 v121, v121
	s_waitcnt vmcnt(0)
	v_mov_b32_e32 v122, v222
	v_mov_b32_e32 v123, v223
	v_lshlrev_b32_e32 v134, 16, v122
	v_and_b32_e32 v135, 0xffff0000, v122
	v_lshlrev_b32_e32 v122, 16, v123
	v_and_b32_e32 v123, 0xffff0000, v123
	v_pk_mul_f32 v[118:119], v[118:119], v[134:135]
	v_pk_mul_f32 v[120:121], v[120:121], v[122:123]
	v_cvt_pk_bf16_f32 v118, v118, v119
	v_cvt_pk_bf16_f32 v119, v120, v121
	v_lshl_add_u64 v[120:121], s[22:23], 0, v[130:131]
	v_lshl_add_u64 v[120:121], v[120:121], 0, s[2:3]
	v_lshl_add_u64 v[120:121], v[120:121], 0, v[188:189]
	v_add_co_u32_e32 v122, vcc, s6, v120
	v_lshl_add_u64 v[124:125], v[120:121], 0, s[14:15]
	s_nop 0
	v_addc_co_u32_e32 v123, vcc, 0, v121, vcc
	global_store_dwordx4 v[122:123], v[112:115], off offset:1536
	global_store_dwordx4 v[124:125], v[116:119], off offset:16
	global_load_dwordx4 v[112:115], v[174:175], off offset:128
	s_nop 0
	s_waitcnt vmcnt(0)
; DI uint2 pk4(float a, float b, float c, float d) { uint2 r; r.x = pk2(a, b); r.y = pk2(c, d); return r; }
; DI float bflo(unsigned v) { return __uint_as_float(v << 16); }
; DI float bfhi(unsigned v) { return __uint_as_float(v & 0xffff0000u); }
; DI float sigmoidf_(float x) { return __builtin_amdgcn_rcpf(1.f + __builtin_amdgcn_exp2f(-LOG2E * x)); }
;   DI u16* r1() const { return (u16*)(ws + O_R1); }
;   DI u16* ysact() const { return (u16*)(ws + O_YSACT); }
;   DI void operator()(f32x16 (&acc)[2][4], int wm, int wn, int lane) const {
;     ...
;     for (int mt = 0; mt < 4; ++mt) {
;       const int tok = m0 + wm * 128 + mt * 32 + r32;
; #pragma unroll
;       for (int nt = 0; nt < 2; ++nt) {
;         uint2 pk[4];
; #pragma unroll
;         for (int q4 = 0; q4 < 4; ++q4) {
;           const int n = n0 + wn * 64 + nt * 32 + q4 * 8 + hh * 4;
;           const float4 bb = *(const float4*)(gb + n);
;           const uint2 ys = *(const uint2*)(c.ysact() + (size_t)tok * 256 + n);
;           pk[q4] = pk4(bflo(ys.x) * sigmoidf_(acc[nt][mt][q4 * 4 + 0] + bb.x), bfhi(ys.x) * sigmoidf_(acc[nt][mt][q4 * 4 + 1] + bb.y),
;                        bflo(ys.y) * sigmoidf_(acc[nt][mt][q4 * 4 + 2] + bb.z), bfhi(ys.y) * sigmoidf_(acc[nt][mt][q4 * 4 + 3] + bb.w));
;         }
;         u16* d_ = c.r1() + (size_t)tok * 1024 + 768 + n0 + wn * 64 + nt * 32 + hh * 16;
;         *(uint4*)d_ = make_uint4(pk[0].x, pk[0].y, pk[1].x, pk[1].y);
;         *(uint4*)(d_ + 8) = make_uint4(pk[2].x, pk[2].y, pk[3].x, pk[3].y);
;       }
	v_add_f32_e32 v96, v96, v112
	v_add_f32_e32 v97, v97, v113
	v_add_f32_e32 v98, v98, v114
	v_add_f32_e32 v99, v99, v115
	v_mul_f32_e32 v96, 0xbfb8aa3b, v96
	v_mul_f32_e32 v97, 0xbfb8aa3b, v97
	v_mul_f32_e32 v98, 0xbfb8aa3b, v98
	v_mul_f32_e32 v99, 0xbfb8aa3b, v99
	v_exp_f32_e32 v96, v96
	v_exp_f32_e32 v97, v97
	v_exp_f32_e32 v98, v98
	v_exp_f32_e32 v99, v99
	v_add_f32_e32 v96, 1.0, v96
	v_add_f32_e32 v97, 1.0, v97
	v_add_f32_e32 v98, 1.0, v98
	v_add_f32_e32 v99, 1.0, v99
	v_rcp_f32_e32 v96, v96
	v_rcp_f32_e32 v97, v97
	v_rcp_f32_e32 v98, v98
	v_rcp_f32_e32 v99, v99
	s_waitcnt vmcnt(0)
	v_mov_b32_e32 v116, v142
	v_mov_b32_e32 v117, v143
	v_lshlrev_b32_e32 v118, 16, v116
	v_and_b32_e32 v119, 0xffff0000, v116
	v_lshlrev_b32_e32 v112, 16, v117
	v_and_b32_e32 v113, 0xffff0000, v117
	v_pk_mul_f32 v[96:97], v[96:97], v[118:119]
	v_pk_mul_f32 v[98:99], v[98:99], v[112:113]
	v_cvt_pk_bf16_f32 v96, v96, v97
	v_cvt_pk_bf16_f32 v97, v98, v99
	global_load_dwordx4 v[112:115], v[174:175], off offset:160
	s_waitcnt vmcnt(0)
	v_add_f32_e32 v100, v100, v112
	s_waitcnt vmcnt(0)
	v_mov_b32_e32 v98, v144
	v_mov_b32_e32 v99, v145
	v_lshlrev_b32_e32 v116, 16, v98
	v_and_b32_e32 v117, 0xffff0000, v98
	v_add_f32_e32 v98, v101, v113
	v_add_f32_e32 v102, v102, v114
	v_add_f32_e32 v103, v103, v115
	v_mul_f32_e32 v100, 0xbfb8aa3b, v100
	v_mul_f32_e32 v98, 0xbfb8aa3b, v98
	v_mul_f32_e32 v102, 0xbfb8aa3b, v102
	v_mul_f32_e32 v103, 0xbfb8aa3b, v103
	v_exp_f32_e32 v100, v100
	v_exp_f32_e32 v98, v98
	v_exp_f32_e32 v102, v102
	v_exp_f32_e32 v103, v103
	v_add_f32_e32 v100, 1.0, v100
	v_add_f32_e32 v98, 1.0, v98
	v_add_f32_e32 v102, 1.0, v102
	v_add_f32_e32 v103, 1.0, v103
	v_rcp_f32_e32 v100, v100
	v_rcp_f32_e32 v101, v98
	v_rcp_f32_e32 v102, v102
	v_rcp_f32_e32 v103, v103
	v_lshlrev_b32_e32 v98, 16, v99
	v_and_b32_e32 v99, 0xffff0000, v99
	v_pk_mul_f32 v[100:101], v[100:101], v[116:117]
	v_pk_mul_f32 v[102:103], v[102:103], v[98:99]
	v_cvt_pk_bf16_f32 v98, v100, v101
	v_cvt_pk_bf16_f32 v99, v102, v103
	global_load_dwordx4 v[100:103], v[174:175], off offset:192
	s_waitcnt vmcnt(0)
	v_add_f32_e32 v100, v104, v100
	v_add_f32_e32 v101, v105, v101
	v_add_f32_e32 v102, v106, v102
	v_add_f32_e32 v103, v107, v103
	v_mul_f32_e32 v100, 0xbfb8aa3b, v100
	v_mul_f32_e32 v101, 0xbfb8aa3b, v101
	v_mul_f32_e32 v102, 0xbfb8aa3b, v102
	v_mul_f32_e32 v103, 0xbfb8aa3b, v103
	v_exp_f32_e32 v100, v100
	v_exp_f32_e32 v101, v101
	v_exp_f32_e32 v102, v102
	v_exp_f32_e32 v103, v103
	v_add_f32_e32 v100, 1.0, v100
	v_add_f32_e32 v101, 1.0, v101
	v_add_f32_e32 v102, 1.0, v102
	v_add_f32_e32 v103, 1.0, v103
	v_rcp_f32_e32 v100, v100
	v_rcp_f32_e32 v101, v101
	v_rcp_f32_e32 v102, v102
	v_rcp_f32_e32 v103, v103
	s_waitcnt vmcnt(0)
	v_mov_b32_e32 v112, v146
	v_mov_b32_e32 v113, v147
	v_lshlrev_b32_e32 v114, 16, v112
	v_and_b32_e32 v115, 0xffff0000, v112
	v_lshlrev_b32_e32 v104, 16, v113
	v_and_b32_e32 v105, 0xffff0000, v113
	v_pk_mul_f32 v[100:101], v[100:101], v[114:115]
	v_pk_mul_f32 v[102:103], v[102:103], v[104:105]
	v_cvt_pk_bf16_f32 v100, v100, v101
	v_cvt_pk_bf16_f32 v101, v102, v103
	global_load_dwordx4 v[102:105], v[174:175], off offset:224
	s_waitcnt vmcnt(0)
	v_add_f32_e32 v102, v108, v102
	v_add_f32_e32 v103, v109, v103
	v_add_f32_e32 v104, v110, v104
	v_add_f32_e32 v105, v111, v105
	v_mul_f32_e32 v102, 0xbfb8aa3b, v102
	v_mul_f32_e32 v103, 0xbfb8aa3b, v103
	v_mul_f32_e32 v104, 0xbfb8aa3b, v104
	v_mul_f32_e32 v105, 0xbfb8aa3b, v105
	v_exp_f32_e32 v102, v102
	v_exp_f32_e32 v103, v103
	v_exp_f32_e32 v104, v104
	v_exp_f32_e32 v105, v105
	v_add_f32_e32 v102, 1.0, v102
	v_add_f32_e32 v103, 1.0, v103
	v_add_f32_e32 v104, 1.0, v104
	v_add_f32_e32 v105, 1.0, v105
	v_rcp_f32_e32 v102, v102
	v_rcp_f32_e32 v103, v103
	v_rcp_f32_e32 v104, v104
	v_rcp_f32_e32 v105, v105
	s_waitcnt vmcnt(0)
	v_mov_b32_e32 v106, v148
	v_mov_b32_e32 v107, v149
	v_lshlrev_b32_e32 v112, 16, v106
	v_and_b32_e32 v113, 0xffff0000, v106
	v_lshlrev_b32_e32 v106, 16, v107
	v_and_b32_e32 v107, 0xffff0000, v107
	v_pk_mul_f32 v[102:103], v[102:103], v[112:113]
	v_pk_mul_f32 v[104:105], v[104:105], v[106:107]
	v_cvt_pk_bf16_f32 v102, v102, v103
	v_cvt_pk_bf16_f32 v103, v104, v105
	v_lshl_add_u64 v[104:105], v[120:121], 0, s[16:17]
	global_store_dwordx4 v[122:123], v[96:99], off offset:1600
	global_store_dwordx4 v[104:105], v[100:103], off offset:16
	global_load_dwordx4 v[100:103], v[174:175], off
	v_or_b32_e32 v96, 32, v132
	v_mov_b32_e32 v97, v165
	v_lshlrev_b64 v[104:105], 9, v[96:97]
	v_lshlrev_b64 v[98:99], 11, v[96:97]
	v_lshl_add_u64 v[96:97], v[176:177], 0, v[104:105]
	global_load_dwordx2 v[216:217], v[96:97], off
	global_load_dwordx2 v[218:219], v[96:97], off offset:16
	global_load_dwordx2 v[220:221], v[96:97], off offset:32
	global_load_dwordx2 v[222:223], v[96:97], off offset:48
	global_load_dwordx2 v[142:143], v[96:97], off offset:64
	global_load_dwordx2 v[144:145], v[96:97], off offset:80
	global_load_dwordx2 v[146:147], v[96:97], off offset:96
	global_load_dwordx2 v[148:149], v[96:97], off offset:112
	s_waitcnt vmcnt(0)
	v_add_f32_e32 v80, v80, v100
	v_add_f32_e32 v81, v81, v101
	v_add_f32_e32 v82, v82, v102
	v_add_f32_e32 v83, v83, v103
	v_mul_f32_e32 v80, 0xbfb8aa3b, v80
	v_mul_f32_e32 v81, 0xbfb8aa3b, v81
	v_mul_f32_e32 v82, 0xbfb8aa3b, v82
	v_mul_f32_e32 v83, 0xbfb8aa3b, v83
	v_exp_f32_e32 v80, v80
	v_exp_f32_e32 v81, v81
	v_exp_f32_e32 v82, v82
	v_exp_f32_e32 v83, v83
	v_add_f32_e32 v80, 1.0, v80
	v_add_f32_e32 v81, 1.0, v81
	v_add_f32_e32 v82, 1.0, v82
	v_add_f32_e32 v83, 1.0, v83
	v_rcp_f32_e32 v80, v80
	v_rcp_f32_e32 v81, v81
	v_rcp_f32_e32 v82, v82
	v_rcp_f32_e32 v83, v83
	s_waitcnt vmcnt(0)
; DI uint2 pk4(float a, float b, float c, float d) { uint2 r; r.x = pk2(a, b); r.y = pk2(c, d); return r; }
; DI float bflo(unsigned v) { return __uint_as_float(v << 16); }
; DI float bfhi(unsigned v) { return __uint_as_float(v & 0xffff0000u); }
; DI float sigmoidf_(float x) { return __builtin_amdgcn_rcpf(1.f + __builtin_amdgcn_exp2f(-LOG2E * x)); }
;   DI u16* r1() const { return (u16*)(ws + O_R1); }
;   DI u16* ysact() const { return (u16*)(ws + O_YSACT); }
;   DI void operator()(f32x16 (&acc)[2][4], int wm, int wn, int lane) const {
;     ...
;     for (int mt = 0; mt < 4; ++mt) {
;       const int tok = m0 + wm * 128 + mt * 32 + r32;
; #pragma unroll
;       for (int nt = 0; nt < 2; ++nt) {
;         uint2 pk[4];
; #pragma unroll
;         for (int q4 = 0; q4 < 4; ++q4) {
;           const int n = n0 + wn * 64 + nt * 32 + q4 * 8 + hh * 4;
;           const float4 bb = *(const float4*)(gb + n);
;           const uint2 ys = *(const uint2*)(c.ysact() + (size_t)tok * 256 + n);
;           pk[q4] = pk4(bflo(ys.x) * sigmoidf_(acc[nt][mt][q4 * 4 + 0] + bb.x), bfhi(ys.x) * sigmoidf_(acc[nt][mt][q4 * 4 + 1] + bb.y),
;                        bflo(ys.y) * sigmoidf_(acc[nt][mt][q4 * 4 + 2] + bb.z), bfhi(ys.y) * sigmoidf_(acc[nt][mt][q4 * 4 + 3] + bb.w));
;         }
;         u16* d_ = c.r1() + (size_t)tok * 1024 + 768 + n0 + wn * 64 + nt * 32 + hh * 16;
;         *(uint4*)d_ = make_uint4(pk[0].x, pk[0].y, pk[1].x, pk[1].y);
;         *(uint4*)(d_ + 8) = make_uint4(pk[2].x, pk[2].y, pk[3].x, pk[3].y);
;       }
	v_mov_b32_e32 v104, v216
	v_mov_b32_e32 v105, v217
	v_lshlrev_b32_e32 v106, 16, v104
	v_and_b32_e32 v107, 0xffff0000, v104
	v_lshlrev_b32_e32 v100, 16, v105
	v_and_b32_e32 v101, 0xffff0000, v105
	v_pk_mul_f32 v[80:81], v[80:81], v[106:107]
	v_pk_mul_f32 v[82:83], v[82:83], v[100:101]
	v_cvt_pk_bf16_f32 v80, v80, v81
	v_cvt_pk_bf16_f32 v81, v82, v83
	global_load_dwordx4 v[100:103], v[174:175], off offset:32
	s_waitcnt vmcnt(0)
	v_add_f32_e32 v84, v84, v100
	s_waitcnt vmcnt(0)
	v_mov_b32_e32 v82, v218
	v_mov_b32_e32 v83, v219
	v_lshlrev_b32_e32 v104, 16, v82
	v_and_b32_e32 v105, 0xffff0000, v82
	v_add_f32_e32 v82, v85, v101
	v_add_f32_e32 v86, v86, v102
	v_add_f32_e32 v87, v87, v103
	v_mul_f32_e32 v84, 0xbfb8aa3b, v84
	v_mul_f32_e32 v82, 0xbfb8aa3b, v82
	v_mul_f32_e32 v86, 0xbfb8aa3b, v86
	v_mul_f32_e32 v87, 0xbfb8aa3b, v87
	v_exp_f32_e32 v84, v84
	v_exp_f32_e32 v82, v82
	v_exp_f32_e32 v86, v86
	v_exp_f32_e32 v87, v87
	v_add_f32_e32 v84, 1.0, v84
	v_add_f32_e32 v82, 1.0, v82
	v_add_f32_e32 v86, 1.0, v86
	v_add_f32_e32 v87, 1.0, v87
	v_rcp_f32_e32 v84, v84
	v_rcp_f32_e32 v85, v82
	v_rcp_f32_e32 v86, v86
	v_rcp_f32_e32 v87, v87
	v_lshlrev_b32_e32 v82, 16, v83
	v_and_b32_e32 v83, 0xffff0000, v83
	v_pk_mul_f32 v[84:85], v[84:85], v[104:105]
	v_pk_mul_f32 v[86:87], v[86:87], v[82:83]
	v_cvt_pk_bf16_f32 v82, v84, v85
	v_cvt_pk_bf16_f32 v83, v86, v87
	global_load_dwordx4 v[84:87], v[174:175], off offset:64
	s_waitcnt vmcnt(0)
	v_add_f32_e32 v84, v88, v84
	v_add_f32_e32 v85, v89, v85
	v_add_f32_e32 v86, v90, v86
	v_add_f32_e32 v87, v91, v87
	v_mul_f32_e32 v84, 0xbfb8aa3b, v84
	v_mul_f32_e32 v85, 0xbfb8aa3b, v85
	v_mul_f32_e32 v86, 0xbfb8aa3b, v86
	v_mul_f32_e32 v87, 0xbfb8aa3b, v87
	v_exp_f32_e32 v84, v84
	v_exp_f32_e32 v85, v85
	v_exp_f32_e32 v86, v86
	v_exp_f32_e32 v87, v87
	v_add_f32_e32 v84, 1.0, v84
	v_add_f32_e32 v85, 1.0, v85
	v_add_f32_e32 v86, 1.0, v86
	v_add_f32_e32 v87, 1.0, v87
	v_rcp_f32_e32 v84, v84
	v_rcp_f32_e32 v85, v85
	v_rcp_f32_e32 v86, v86
	v_rcp_f32_e32 v87, v87
	s_waitcnt vmcnt(0)
	v_mov_b32_e32 v100, v220
	v_mov_b32_e32 v101, v221
	v_lshlrev_b32_e32 v102, 16, v100
	v_and_b32_e32 v103, 0xffff0000, v100
	v_lshlrev_b32_e32 v88, 16, v101
	v_and_b32_e32 v89, 0xffff0000, v101
	v_pk_mul_f32 v[84:85], v[84:85], v[102:103]
	v_pk_mul_f32 v[86:87], v[86:87], v[88:89]
	v_cvt_pk_bf16_f32 v84, v84, v85
	v_cvt_pk_bf16_f32 v85, v86, v87
	global_load_dwordx4 v[86:89], v[174:175], off offset:96
	s_waitcnt vmcnt(0)
	v_add_f32_e32 v86, v92, v86
	v_add_f32_e32 v87, v93, v87
	v_add_f32_e32 v88, v94, v88
	v_add_f32_e32 v89, v95, v89
	v_mul_f32_e32 v86, 0xbfb8aa3b, v86
	v_mul_f32_e32 v87, 0xbfb8aa3b, v87
	v_mul_f32_e32 v88, 0xbfb8aa3b, v88
	v_mul_f32_e32 v89, 0xbfb8aa3b, v89
	v_exp_f32_e32 v86, v86
	v_exp_f32_e32 v87, v87
	v_exp_f32_e32 v88, v88
	v_exp_f32_e32 v89, v89
	v_add_f32_e32 v86, 1.0, v86
	v_add_f32_e32 v87, 1.0, v87
	v_add_f32_e32 v88, 1.0, v88
	v_add_f32_e32 v89, 1.0, v89
	v_rcp_f32_e32 v86, v86
	v_rcp_f32_e32 v87, v87
	v_rcp_f32_e32 v88, v88
	v_rcp_f32_e32 v89, v89
	s_waitcnt vmcnt(0)
	v_mov_b32_e32 v90, v222
	v_mov_b32_e32 v91, v223
	v_lshlrev_b32_e32 v100, 16, v90
	v_and_b32_e32 v101, 0xffff0000, v90
	v_lshlrev_b32_e32 v90, 16, v91
	v_and_b32_e32 v91, 0xffff0000, v91
	v_pk_mul_f32 v[86:87], v[86:87], v[100:101]
	v_pk_mul_f32 v[88:89], v[88:89], v[90:91]
	v_cvt_pk_bf16_f32 v86, v86, v87
	v_cvt_pk_bf16_f32 v87, v88, v89
	v_lshl_add_u64 v[88:89], s[22:23], 0, v[98:99]
	v_lshl_add_u64 v[88:89], v[88:89], 0, s[2:3]
	v_lshl_add_u64 v[88:89], v[88:89], 0, v[188:189]
	v_add_co_u32_e32 v90, vcc, s6, v88
	v_lshl_add_u64 v[92:93], v[88:89], 0, s[14:15]
	s_nop 0
	v_addc_co_u32_e32 v91, vcc, 0, v89, vcc
	global_store_dwordx4 v[90:91], v[80:83], off offset:1536
	global_store_dwordx4 v[92:93], v[84:87], off offset:16
	global_load_dwordx4 v[80:83], v[174:175], off offset:128
	s_nop 0
	s_waitcnt vmcnt(0)
	v_add_f32_e32 v64, v64, v80
	v_add_f32_e32 v65, v65, v81
	v_add_f32_e32 v66, v66, v82
	v_add_f32_e32 v67, v67, v83
	v_mul_f32_e32 v64, 0xbfb8aa3b, v64
	v_mul_f32_e32 v65, 0xbfb8aa3b, v65
	v_mul_f32_e32 v66, 0xbfb8aa3b, v66
	v_mul_f32_e32 v67, 0xbfb8aa3b, v67
	v_exp_f32_e32 v64, v64
	v_exp_f32_e32 v65, v65
	v_exp_f32_e32 v66, v66
	v_exp_f32_e32 v67, v67
	v_add_f32_e32 v64, 1.0, v64
	v_add_f32_e32 v65, 1.0, v65
	v_add_f32_e32 v66, 1.0, v66
	v_add_f32_e32 v67, 1.0, v67
	v_rcp_f32_e32 v64, v64
	v_rcp_f32_e32 v65, v65
	v_rcp_f32_e32 v66, v66
	v_rcp_f32_e32 v67, v67
	s_waitcnt vmcnt(0)
	v_mov_b32_e32 v84, v142
	v_mov_b32_e32 v85, v143
	v_lshlrev_b32_e32 v86, 16, v84
	v_and_b32_e32 v87, 0xffff0000, v84
	v_lshlrev_b32_e32 v80, 16, v85
	v_and_b32_e32 v81, 0xffff0000, v85
	v_pk_mul_f32 v[64:65], v[64:65], v[86:87]
	v_pk_mul_f32 v[66:67], v[66:67], v[80:81]
	v_cvt_pk_bf16_f32 v64, v64, v65
	v_cvt_pk_bf16_f32 v65, v66, v67
	global_load_dwordx4 v[80:83], v[174:175], off offset:160
	s_waitcnt vmcnt(0)
	v_add_f32_e32 v68, v68, v80
	s_waitcnt vmcnt(0)
	v_mov_b32_e32 v66, v144
	v_mov_b32_e32 v67, v145
	v_lshlrev_b32_e32 v84, 16, v66
	v_and_b32_e32 v85, 0xffff0000, v66
	v_add_f32_e32 v66, v69, v81
	v_add_f32_e32 v70, v70, v82
	v_add_f32_e32 v71, v71, v83
	v_mul_f32_e32 v68, 0xbfb8aa3b, v68
	v_mul_f32_e32 v66, 0xbfb8aa3b, v66
	v_mul_f32_e32 v70, 0xbfb8aa3b, v70
	v_mul_f32_e32 v71, 0xbfb8aa3b, v71
	v_exp_f32_e32 v68, v68
	v_exp_f32_e32 v66, v66
	v_exp_f32_e32 v70, v70
	v_exp_f32_e32 v71, v71
	v_add_f32_e32 v68, 1.0, v68
	v_add_f32_e32 v66, 1.0, v66
	v_add_f32_e32 v70, 1.0, v70
	v_add_f32_e32 v71, 1.0, v71
	v_rcp_f32_e32 v68, v68
	v_rcp_f32_e32 v69, v66
	v_rcp_f32_e32 v70, v70
	v_rcp_f32_e32 v71, v71
	v_lshlrev_b32_e32 v66, 16, v67
	v_and_b32_e32 v67, 0xffff0000, v67
	v_pk_mul_f32 v[68:69], v[68:69], v[84:85]
	v_pk_mul_f32 v[70:71], v[70:71], v[66:67]
	v_cvt_pk_bf16_f32 v66, v68, v69
	v_cvt_pk_bf16_f32 v67, v70, v71
	global_load_dwordx4 v[68:71], v[174:175], off offset:192
	s_waitcnt vmcnt(0)
; DI uint2 pk4(float a, float b, float c, float d) { uint2 r; r.x = pk2(a, b); r.y = pk2(c, d); return r; }
; DI float bflo(unsigned v) { return __uint_as_float(v << 16); }
; DI float bfhi(unsigned v) { return __uint_as_float(v & 0xffff0000u); }
; DI float sigmoidf_(float x) { return __builtin_amdgcn_rcpf(1.f + __builtin_amdgcn_exp2f(-LOG2E * x)); }
;   DI u16* r1() const { return (u16*)(ws + O_R1); }
;   DI u16* ysact() const { return (u16*)(ws + O_YSACT); }
;   DI void operator()(f32x16 (&acc)[2][4], int wm, int wn, int lane) const {
;     ...
;     for (int mt = 0; mt < 4; ++mt) {
;       const int tok = m0 + wm * 128 + mt * 32 + r32;
; #pragma unroll
;       for (int nt = 0; nt < 2; ++nt) {
;         uint2 pk[4];
; #pragma unroll
;         for (int q4 = 0; q4 < 4; ++q4) {
;           const int n = n0 + wn * 64 + nt * 32 + q4 * 8 + hh * 4;
;           const float4 bb = *(const float4*)(gb + n);
;           const uint2 ys = *(const uint2*)(c.ysact() + (size_t)tok * 256 + n);
;           pk[q4] = pk4(bflo(ys.x) * sigmoidf_(acc[nt][mt][q4 * 4 + 0] + bb.x), bfhi(ys.x) * sigmoidf_(acc[nt][mt][q4 * 4 + 1] + bb.y),
;                        bflo(ys.y) * sigmoidf_(acc[nt][mt][q4 * 4 + 2] + bb.z), bfhi(ys.y) * sigmoidf_(acc[nt][mt][q4 * 4 + 3] + bb.w));
;         }
;         u16* d_ = c.r1() + (size_t)tok * 1024 + 768 + n0 + wn * 64 + nt * 32 + hh * 16;
;         *(uint4*)d_ = make_uint4(pk[0].x, pk[0].y, pk[1].x, pk[1].y);
;         *(uint4*)(d_ + 8) = make_uint4(pk[2].x, pk[2].y, pk[3].x, pk[3].y);
;       }
	v_add_f32_e32 v68, v72, v68
	v_add_f32_e32 v69, v73, v69
	v_add_f32_e32 v70, v74, v70
	v_add_f32_e32 v71, v75, v71
	v_mul_f32_e32 v68, 0xbfb8aa3b, v68
	v_mul_f32_e32 v69, 0xbfb8aa3b, v69
	v_mul_f32_e32 v70, 0xbfb8aa3b, v70
	v_mul_f32_e32 v71, 0xbfb8aa3b, v71
	v_exp_f32_e32 v68, v68
	v_exp_f32_e32 v69, v69
	v_exp_f32_e32 v70, v70
	v_exp_f32_e32 v71, v71
	v_add_f32_e32 v68, 1.0, v68
	v_add_f32_e32 v69, 1.0, v69
	v_add_f32_e32 v70, 1.0, v70
	v_add_f32_e32 v71, 1.0, v71
	v_rcp_f32_e32 v68, v68
	v_rcp_f32_e32 v69, v69
	v_rcp_f32_e32 v70, v70
	v_rcp_f32_e32 v71, v71
	s_waitcnt vmcnt(0)
	v_mov_b32_e32 v80, v146
	v_mov_b32_e32 v81, v147
	v_lshlrev_b32_e32 v82, 16, v80
	v_and_b32_e32 v83, 0xffff0000, v80
	v_lshlrev_b32_e32 v72, 16, v81
	v_and_b32_e32 v73, 0xffff0000, v81
	v_pk_mul_f32 v[68:69], v[68:69], v[82:83]
	v_pk_mul_f32 v[70:71], v[70:71], v[72:73]
	v_cvt_pk_bf16_f32 v68, v68, v69
	v_cvt_pk_bf16_f32 v69, v70, v71
	global_load_dwordx4 v[70:73], v[174:175], off offset:224
	s_waitcnt vmcnt(0)
	v_add_f32_e32 v70, v76, v70
	v_add_f32_e32 v71, v77, v71
	v_add_f32_e32 v72, v78, v72
	v_add_f32_e32 v73, v79, v73
	v_mul_f32_e32 v70, 0xbfb8aa3b, v70
	v_mul_f32_e32 v71, 0xbfb8aa3b, v71
	v_mul_f32_e32 v72, 0xbfb8aa3b, v72
	v_mul_f32_e32 v73, 0xbfb8aa3b, v73
	v_exp_f32_e32 v70, v70
	v_exp_f32_e32 v71, v71
	v_exp_f32_e32 v72, v72
	v_exp_f32_e32 v73, v73
	v_add_f32_e32 v70, 1.0, v70
	v_add_f32_e32 v71, 1.0, v71
	v_add_f32_e32 v72, 1.0, v72
	v_add_f32_e32 v73, 1.0, v73
	v_rcp_f32_e32 v70, v70
	v_rcp_f32_e32 v71, v71
	v_rcp_f32_e32 v72, v72
	v_rcp_f32_e32 v73, v73
	s_waitcnt vmcnt(0)
	v_mov_b32_e32 v74, v148
	v_mov_b32_e32 v75, v149
	v_lshlrev_b32_e32 v80, 16, v74
	v_and_b32_e32 v81, 0xffff0000, v74
	v_lshlrev_b32_e32 v74, 16, v75
	v_and_b32_e32 v75, 0xffff0000, v75
	v_pk_mul_f32 v[70:71], v[70:71], v[80:81]
	v_pk_mul_f32 v[72:73], v[72:73], v[74:75]
	v_cvt_pk_bf16_f32 v70, v70, v71
	v_cvt_pk_bf16_f32 v71, v72, v73
	v_lshl_add_u64 v[72:73], v[88:89], 0, s[16:17]
	global_store_dwordx4 v[90:91], v[64:67], off offset:1600
	global_store_dwordx4 v[72:73], v[68:71], off offset:16
	global_load_dwordx4 v[68:71], v[174:175], off
	v_or_b32_e32 v64, 64, v132
	v_mov_b32_e32 v65, v165
	v_lshlrev_b64 v[72:73], 9, v[64:65]
	v_lshlrev_b64 v[66:67], 11, v[64:65]
	v_lshl_add_u64 v[64:65], v[176:177], 0, v[72:73]
	global_load_dwordx2 v[216:217], v[64:65], off
	global_load_dwordx2 v[218:219], v[64:65], off offset:16
	global_load_dwordx2 v[220:221], v[64:65], off offset:32
	global_load_dwordx2 v[222:223], v[64:65], off offset:48
	global_load_dwordx2 v[142:143], v[64:65], off offset:64
	global_load_dwordx2 v[144:145], v[64:65], off offset:80
	global_load_dwordx2 v[146:147], v[64:65], off offset:96
	global_load_dwordx2 v[148:149], v[64:65], off offset:112
	s_waitcnt vmcnt(0)
	v_add_f32_e32 v48, v48, v68
	v_add_f32_e32 v49, v49, v69
	v_add_f32_e32 v50, v50, v70
	v_add_f32_e32 v51, v51, v71
	v_mul_f32_e32 v48, 0xbfb8aa3b, v48
	v_mul_f32_e32 v49, 0xbfb8aa3b, v49
	v_mul_f32_e32 v50, 0xbfb8aa3b, v50
	v_mul_f32_e32 v51, 0xbfb8aa3b, v51
	v_exp_f32_e32 v48, v48
	v_exp_f32_e32 v49, v49
	v_exp_f32_e32 v50, v50
	v_exp_f32_e32 v51, v51
	v_add_f32_e32 v48, 1.0, v48
	v_add_f32_e32 v49, 1.0, v49
	v_add_f32_e32 v50, 1.0, v50
	v_add_f32_e32 v51, 1.0, v51
	v_rcp_f32_e32 v48, v48
	v_rcp_f32_e32 v49, v49
	v_rcp_f32_e32 v50, v50
	v_rcp_f32_e32 v51, v51
	s_waitcnt vmcnt(0)
	v_mov_b32_e32 v72, v216
	v_mov_b32_e32 v73, v217
	v_lshlrev_b32_e32 v74, 16, v72
	v_and_b32_e32 v75, 0xffff0000, v72
	v_lshlrev_b32_e32 v68, 16, v73
	v_and_b32_e32 v69, 0xffff0000, v73
	v_pk_mul_f32 v[48:49], v[48:49], v[74:75]
	v_pk_mul_f32 v[50:51], v[50:51], v[68:69]
	v_cvt_pk_bf16_f32 v48, v48, v49
	v_cvt_pk_bf16_f32 v49, v50, v51
	global_load_dwordx4 v[68:71], v[174:175], off offset:32
	s_waitcnt vmcnt(0)
	v_add_f32_e32 v52, v52, v68
	s_waitcnt vmcnt(0)
	v_mov_b32_e32 v50, v218
	v_mov_b32_e32 v51, v219
	v_lshlrev_b32_e32 v72, 16, v50
	v_and_b32_e32 v73, 0xffff0000, v50
	v_add_f32_e32 v50, v53, v69
	v_add_f32_e32 v54, v54, v70
	v_add_f32_e32 v55, v55, v71
	v_mul_f32_e32 v52, 0xbfb8aa3b, v52
	v_mul_f32_e32 v50, 0xbfb8aa3b, v50
	v_mul_f32_e32 v54, 0xbfb8aa3b, v54
	v_mul_f32_e32 v55, 0xbfb8aa3b, v55
	v_exp_f32_e32 v52, v52
	v_exp_f32_e32 v50, v50
	v_exp_f32_e32 v54, v54
	v_exp_f32_e32 v55, v55
	v_add_f32_e32 v52, 1.0, v52
	v_add_f32_e32 v50, 1.0, v50
	v_add_f32_e32 v54, 1.0, v54
	v_add_f32_e32 v55, 1.0, v55
	v_rcp_f32_e32 v52, v52
	v_rcp_f32_e32 v53, v50
	v_rcp_f32_e32 v54, v54
	v_rcp_f32_e32 v55, v55
	v_lshlrev_b32_e32 v50, 16, v51
	v_and_b32_e32 v51, 0xffff0000, v51
	v_pk_mul_f32 v[52:53], v[52:53], v[72:73]
	v_pk_mul_f32 v[54:55], v[54:55], v[50:51]
	v_cvt_pk_bf16_f32 v50, v52, v53
	v_cvt_pk_bf16_f32 v51, v54, v55
	global_load_dwordx4 v[52:55], v[174:175], off offset:64
	s_waitcnt vmcnt(0)
	v_add_f32_e32 v52, v56, v52
	v_add_f32_e32 v53, v57, v53
	v_add_f32_e32 v54, v58, v54
	v_add_f32_e32 v55, v59, v55
	v_mul_f32_e32 v52, 0xbfb8aa3b, v52
	v_mul_f32_e32 v53, 0xbfb8aa3b, v53
	v_mul_f32_e32 v54, 0xbfb8aa3b, v54
	v_mul_f32_e32 v55, 0xbfb8aa3b, v55
	v_exp_f32_e32 v52, v52
	v_exp_f32_e32 v53, v53
	v_exp_f32_e32 v54, v54
	v_exp_f32_e32 v55, v55
	v_add_f32_e32 v52, 1.0, v52
	v_add_f32_e32 v53, 1.0, v53
	v_add_f32_e32 v54, 1.0, v54
	v_add_f32_e32 v55, 1.0, v55
	v_rcp_f32_e32 v52, v52
	v_rcp_f32_e32 v53, v53
	v_rcp_f32_e32 v54, v54
	v_rcp_f32_e32 v55, v55
	s_waitcnt vmcnt(0)
	v_mov_b32_e32 v68, v220
	v_mov_b32_e32 v69, v221
	v_lshlrev_b32_e32 v70, 16, v68
	v_and_b32_e32 v71, 0xffff0000, v68
	v_lshlrev_b32_e32 v56, 16, v69
	v_and_b32_e32 v57, 0xffff0000, v69
	v_pk_mul_f32 v[52:53], v[52:53], v[70:71]
	v_pk_mul_f32 v[54:55], v[54:55], v[56:57]
	v_cvt_pk_bf16_f32 v52, v52, v53
	v_cvt_pk_bf16_f32 v53, v54, v55
	global_load_dwordx4 v[54:57], v[174:175], off offset:96
	s_waitcnt vmcnt(0)
; DI uint2 pk4(float a, float b, float c, float d) { uint2 r; r.x = pk2(a, b); r.y = pk2(c, d); return r; }
; DI float bflo(unsigned v) { return __uint_as_float(v << 16); }
; DI float bfhi(unsigned v) { return __uint_as_float(v & 0xffff0000u); }
; DI float sigmoidf_(float x) { return __builtin_amdgcn_rcpf(1.f + __builtin_amdgcn_exp2f(-LOG2E * x)); }
;   DI u16* r1() const { return (u16*)(ws + O_R1); }
;   DI u16* ysact() const { return (u16*)(ws + O_YSACT); }
;   DI void operator()(f32x16 (&acc)[2][4], int wm, int wn, int lane) const {
;     ...
;     for (int mt = 0; mt < 4; ++mt) {
;       const int tok = m0 + wm * 128 + mt * 32 + r32;
; #pragma unroll
;       for (int nt = 0; nt < 2; ++nt) {
;         uint2 pk[4];
; #pragma unroll
;         for (int q4 = 0; q4 < 4; ++q4) {
;           const int n = n0 + wn * 64 + nt * 32 + q4 * 8 + hh * 4;
;           const float4 bb = *(const float4*)(gb + n);
;           const uint2 ys = *(const uint2*)(c.ysact() + (size_t)tok * 256 + n);
;           pk[q4] = pk4(bflo(ys.x) * sigmoidf_(acc[nt][mt][q4 * 4 + 0] + bb.x), bfhi(ys.x) * sigmoidf_(acc[nt][mt][q4 * 4 + 1] + bb.y),
;                        bflo(ys.y) * sigmoidf_(acc[nt][mt][q4 * 4 + 2] + bb.z), bfhi(ys.y) * sigmoidf_(acc[nt][mt][q4 * 4 + 3] + bb.w));
;         }
;         u16* d_ = c.r1() + (size_t)tok * 1024 + 768 + n0 + wn * 64 + nt * 32 + hh * 16;
;         *(uint4*)d_ = make_uint4(pk[0].x, pk[0].y, pk[1].x, pk[1].y);
;         *(uint4*)(d_ + 8) = make_uint4(pk[2].x, pk[2].y, pk[3].x, pk[3].y);
;       }
	v_add_f32_e32 v54, v60, v54
	v_add_f32_e32 v55, v61, v55
	v_add_f32_e32 v56, v62, v56
	v_add_f32_e32 v57, v63, v57
	v_mul_f32_e32 v54, 0xbfb8aa3b, v54
	v_mul_f32_e32 v55, 0xbfb8aa3b, v55
	v_mul_f32_e32 v56, 0xbfb8aa3b, v56
	v_mul_f32_e32 v57, 0xbfb8aa3b, v57
	v_exp_f32_e32 v54, v54
	v_exp_f32_e32 v55, v55
	v_exp_f32_e32 v56, v56
	v_exp_f32_e32 v57, v57
	v_add_f32_e32 v54, 1.0, v54
	v_add_f32_e32 v55, 1.0, v55
	v_add_f32_e32 v56, 1.0, v56
	v_add_f32_e32 v57, 1.0, v57
	v_rcp_f32_e32 v54, v54
	v_rcp_f32_e32 v55, v55
	v_rcp_f32_e32 v56, v56
	v_rcp_f32_e32 v57, v57
	s_waitcnt vmcnt(0)
	v_mov_b32_e32 v58, v222
	v_mov_b32_e32 v59, v223
	v_lshlrev_b32_e32 v68, 16, v58
	v_and_b32_e32 v69, 0xffff0000, v58
	v_lshlrev_b32_e32 v58, 16, v59
	v_and_b32_e32 v59, 0xffff0000, v59
	v_pk_mul_f32 v[54:55], v[54:55], v[68:69]
	v_pk_mul_f32 v[56:57], v[56:57], v[58:59]
	v_cvt_pk_bf16_f32 v54, v54, v55
	v_cvt_pk_bf16_f32 v55, v56, v57
	v_lshl_add_u64 v[56:57], s[22:23], 0, v[66:67]
	v_lshl_add_u64 v[56:57], v[56:57], 0, s[2:3]
	v_lshl_add_u64 v[56:57], v[56:57], 0, v[188:189]
	v_add_co_u32_e32 v58, vcc, s6, v56
	v_lshl_add_u64 v[60:61], v[56:57], 0, s[14:15]
	s_nop 0
	v_addc_co_u32_e32 v59, vcc, 0, v57, vcc
	global_store_dwordx4 v[58:59], v[48:51], off offset:1536
	global_store_dwordx4 v[60:61], v[52:55], off offset:16
	global_load_dwordx4 v[48:51], v[174:175], off offset:128
	s_nop 0
	s_waitcnt vmcnt(0)
	v_add_f32_e32 v32, v32, v48
	v_add_f32_e32 v33, v33, v49
	v_add_f32_e32 v34, v34, v50
	v_add_f32_e32 v35, v35, v51
	v_mul_f32_e32 v32, 0xbfb8aa3b, v32
	v_mul_f32_e32 v33, 0xbfb8aa3b, v33
	v_mul_f32_e32 v34, 0xbfb8aa3b, v34
	v_mul_f32_e32 v35, 0xbfb8aa3b, v35
	v_exp_f32_e32 v32, v32
	v_exp_f32_e32 v33, v33
	v_exp_f32_e32 v34, v34
	v_exp_f32_e32 v35, v35
	v_add_f32_e32 v32, 1.0, v32
	v_add_f32_e32 v33, 1.0, v33
	v_add_f32_e32 v34, 1.0, v34
	v_add_f32_e32 v35, 1.0, v35
	v_rcp_f32_e32 v32, v32
	v_rcp_f32_e32 v33, v33
	v_rcp_f32_e32 v34, v34
	v_rcp_f32_e32 v35, v35
	s_waitcnt vmcnt(0)
	v_mov_b32_e32 v52, v142
	v_mov_b32_e32 v53, v143
	v_lshlrev_b32_e32 v54, 16, v52
	v_and_b32_e32 v55, 0xffff0000, v52
	v_lshlrev_b32_e32 v48, 16, v53
	v_and_b32_e32 v49, 0xffff0000, v53
	v_pk_mul_f32 v[32:33], v[32:33], v[54:55]
	v_pk_mul_f32 v[34:35], v[34:35], v[48:49]
	v_cvt_pk_bf16_f32 v32, v32, v33
	v_cvt_pk_bf16_f32 v33, v34, v35
	global_load_dwordx4 v[48:51], v[174:175], off offset:160
	s_waitcnt vmcnt(0)
	v_add_f32_e32 v36, v36, v48
	s_waitcnt vmcnt(0)
	v_mov_b32_e32 v34, v144
	v_mov_b32_e32 v35, v145
	v_lshlrev_b32_e32 v52, 16, v34
	v_and_b32_e32 v53, 0xffff0000, v34
	v_add_f32_e32 v34, v37, v49
	v_add_f32_e32 v38, v38, v50
	v_add_f32_e32 v39, v39, v51
	v_mul_f32_e32 v36, 0xbfb8aa3b, v36
	v_mul_f32_e32 v34, 0xbfb8aa3b, v34
	v_mul_f32_e32 v38, 0xbfb8aa3b, v38
	v_mul_f32_e32 v39, 0xbfb8aa3b, v39
	v_exp_f32_e32 v36, v36
	v_exp_f32_e32 v34, v34
	v_exp_f32_e32 v38, v38
	v_exp_f32_e32 v39, v39
	v_add_f32_e32 v36, 1.0, v36
	v_add_f32_e32 v34, 1.0, v34
	v_add_f32_e32 v38, 1.0, v38
	v_add_f32_e32 v39, 1.0, v39
	v_rcp_f32_e32 v36, v36
	v_rcp_f32_e32 v37, v34
	v_rcp_f32_e32 v38, v38
	v_rcp_f32_e32 v39, v39
	v_lshlrev_b32_e32 v34, 16, v35
	v_and_b32_e32 v35, 0xffff0000, v35
	v_pk_mul_f32 v[36:37], v[36:37], v[52:53]
	v_pk_mul_f32 v[38:39], v[38:39], v[34:35]
	v_cvt_pk_bf16_f32 v34, v36, v37
	v_cvt_pk_bf16_f32 v35, v38, v39
	global_load_dwordx4 v[36:39], v[174:175], off offset:192
	s_waitcnt vmcnt(0)
	v_add_f32_e32 v36, v40, v36
	v_add_f32_e32 v37, v41, v37
	v_add_f32_e32 v38, v42, v38
	v_add_f32_e32 v39, v43, v39
	v_mul_f32_e32 v36, 0xbfb8aa3b, v36
	v_mul_f32_e32 v37, 0xbfb8aa3b, v37
	v_mul_f32_e32 v38, 0xbfb8aa3b, v38
	v_mul_f32_e32 v39, 0xbfb8aa3b, v39
	v_exp_f32_e32 v36, v36
	v_exp_f32_e32 v37, v37
	v_exp_f32_e32 v38, v38
	v_exp_f32_e32 v39, v39
	v_add_f32_e32 v36, 1.0, v36
	v_add_f32_e32 v37, 1.0, v37
	v_add_f32_e32 v38, 1.0, v38
	v_add_f32_e32 v39, 1.0, v39
	v_rcp_f32_e32 v36, v36
	v_rcp_f32_e32 v37, v37
	v_rcp_f32_e32 v38, v38
	v_rcp_f32_e32 v39, v39
	s_waitcnt vmcnt(0)
	v_mov_b32_e32 v48, v146
	v_mov_b32_e32 v49, v147
	v_lshlrev_b32_e32 v50, 16, v48
	v_and_b32_e32 v51, 0xffff0000, v48
	v_lshlrev_b32_e32 v40, 16, v49
	v_and_b32_e32 v41, 0xffff0000, v49
	v_pk_mul_f32 v[36:37], v[36:37], v[50:51]
	v_pk_mul_f32 v[38:39], v[38:39], v[40:41]
	v_cvt_pk_bf16_f32 v36, v36, v37
	v_cvt_pk_bf16_f32 v37, v38, v39
	global_load_dwordx4 v[38:41], v[174:175], off offset:224
	s_waitcnt vmcnt(0)
	v_add_f32_e32 v38, v44, v38
	v_add_f32_e32 v39, v45, v39
	v_add_f32_e32 v40, v46, v40
	v_add_f32_e32 v41, v47, v41
	v_mul_f32_e32 v38, 0xbfb8aa3b, v38
	v_mul_f32_e32 v39, 0xbfb8aa3b, v39
	v_mul_f32_e32 v40, 0xbfb8aa3b, v40
	v_mul_f32_e32 v41, 0xbfb8aa3b, v41
	v_exp_f32_e32 v38, v38
	v_exp_f32_e32 v39, v39
	v_exp_f32_e32 v40, v40
	v_exp_f32_e32 v41, v41
	v_add_f32_e32 v38, 1.0, v38
	v_add_f32_e32 v39, 1.0, v39
	v_add_f32_e32 v40, 1.0, v40
	v_add_f32_e32 v41, 1.0, v41
	v_rcp_f32_e32 v38, v38
	v_rcp_f32_e32 v39, v39
	v_rcp_f32_e32 v40, v40
	v_rcp_f32_e32 v41, v41
	s_waitcnt vmcnt(0)
	v_mov_b32_e32 v42, v148
	v_mov_b32_e32 v43, v149
	v_lshlrev_b32_e32 v48, 16, v42
	v_and_b32_e32 v49, 0xffff0000, v42
	v_lshlrev_b32_e32 v42, 16, v43
	v_and_b32_e32 v43, 0xffff0000, v43
	v_pk_mul_f32 v[38:39], v[38:39], v[48:49]
	v_pk_mul_f32 v[40:41], v[40:41], v[42:43]
	v_cvt_pk_bf16_f32 v38, v38, v39
	v_cvt_pk_bf16_f32 v39, v40, v41
	v_lshl_add_u64 v[40:41], v[56:57], 0, s[16:17]
	global_store_dwordx4 v[58:59], v[32:35], off offset:1600
	global_store_dwordx4 v[40:41], v[36:39], off offset:16
	global_load_dwordx4 v[36:39], v[174:175], off
	v_or_b32_e32 v32, 0x60, v132
	v_mov_b32_e32 v33, v165
	v_lshlrev_b64 v[40:41], 9, v[32:33]
	v_lshlrev_b64 v[34:35], 11, v[32:33]
	v_lshl_add_u64 v[32:33], v[176:177], 0, v[40:41]
	global_load_dwordx2 v[216:217], v[32:33], off
	global_load_dwordx2 v[218:219], v[32:33], off offset:16
	global_load_dwordx2 v[220:221], v[32:33], off offset:32
	global_load_dwordx2 v[222:223], v[32:33], off offset:48
	global_load_dwordx2 v[142:143], v[32:33], off offset:64
	global_load_dwordx2 v[144:145], v[32:33], off offset:80
	global_load_dwordx2 v[146:147], v[32:33], off offset:96
	global_load_dwordx2 v[148:149], v[32:33], off offset:112
	s_waitcnt vmcnt(0)
; DI uint2 pk4(float a, float b, float c, float d) { uint2 r; r.x = pk2(a, b); r.y = pk2(c, d); return r; }
; DI float bflo(unsigned v) { return __uint_as_float(v << 16); }
; DI float bfhi(unsigned v) { return __uint_as_float(v & 0xffff0000u); }
; DI float sigmoidf_(float x) { return __builtin_amdgcn_rcpf(1.f + __builtin_amdgcn_exp2f(-LOG2E * x)); }
;   DI u16* r1() const { return (u16*)(ws + O_R1); }
;   DI u16* ysact() const { return (u16*)(ws + O_YSACT); }
;   DI void operator()(f32x16 (&acc)[2][4], int wm, int wn, int lane) const {
;     ...
;     for (int mt = 0; mt < 4; ++mt) {
;       const int tok = m0 + wm * 128 + mt * 32 + r32;
; #pragma unroll
;       for (int nt = 0; nt < 2; ++nt) {
;         uint2 pk[4];
; #pragma unroll
;         for (int q4 = 0; q4 < 4; ++q4) {
;           const int n = n0 + wn * 64 + nt * 32 + q4 * 8 + hh * 4;
;           const float4 bb = *(const float4*)(gb + n);
;           const uint2 ys = *(const uint2*)(c.ysact() + (size_t)tok * 256 + n);
;           pk[q4] = pk4(bflo(ys.x) * sigmoidf_(acc[nt][mt][q4 * 4 + 0] + bb.x), bfhi(ys.x) * sigmoidf_(acc[nt][mt][q4 * 4 + 1] + bb.y),
;                        bflo(ys.y) * sigmoidf_(acc[nt][mt][q4 * 4 + 2] + bb.z), bfhi(ys.y) * sigmoidf_(acc[nt][mt][q4 * 4 + 3] + bb.w));
;         }
;         u16* d_ = c.r1() + (size_t)tok * 1024 + 768 + n0 + wn * 64 + nt * 32 + hh * 16;
;         *(uint4*)d_ = make_uint4(pk[0].x, pk[0].y, pk[1].x, pk[1].y);
;         *(uint4*)(d_ + 8) = make_uint4(pk[2].x, pk[2].y, pk[3].x, pk[3].y);
;       }
	v_add_f32_e32 v16, v16, v36
	v_add_f32_e32 v17, v17, v37
	v_add_f32_e32 v18, v18, v38
	v_add_f32_e32 v19, v19, v39
	v_mul_f32_e32 v16, 0xbfb8aa3b, v16
	v_mul_f32_e32 v17, 0xbfb8aa3b, v17
	v_mul_f32_e32 v18, 0xbfb8aa3b, v18
	v_mul_f32_e32 v19, 0xbfb8aa3b, v19
	v_exp_f32_e32 v16, v16
	v_exp_f32_e32 v17, v17
	v_exp_f32_e32 v18, v18
	v_exp_f32_e32 v19, v19
	v_add_f32_e32 v16, 1.0, v16
	v_add_f32_e32 v17, 1.0, v17
	v_add_f32_e32 v18, 1.0, v18
	v_add_f32_e32 v19, 1.0, v19
	v_rcp_f32_e32 v16, v16
	v_rcp_f32_e32 v17, v17
	v_rcp_f32_e32 v18, v18
	v_rcp_f32_e32 v19, v19
	s_waitcnt vmcnt(0)
	v_mov_b32_e32 v40, v216
	v_mov_b32_e32 v41, v217
	v_lshlrev_b32_e32 v42, 16, v40
	v_and_b32_e32 v43, 0xffff0000, v40
	v_lshlrev_b32_e32 v36, 16, v41
	v_and_b32_e32 v37, 0xffff0000, v41
	v_pk_mul_f32 v[16:17], v[16:17], v[42:43]
	v_pk_mul_f32 v[18:19], v[18:19], v[36:37]
	v_cvt_pk_bf16_f32 v16, v16, v17
	v_cvt_pk_bf16_f32 v17, v18, v19
	global_load_dwordx4 v[36:39], v[174:175], off offset:32
	s_waitcnt vmcnt(0)
	v_add_f32_e32 v20, v20, v36
	s_waitcnt vmcnt(0)
	v_mov_b32_e32 v18, v218
	v_mov_b32_e32 v19, v219
	v_lshlrev_b32_e32 v40, 16, v18
	v_and_b32_e32 v41, 0xffff0000, v18
	v_add_f32_e32 v18, v21, v37
	v_add_f32_e32 v22, v22, v38
	v_add_f32_e32 v23, v23, v39
	v_mul_f32_e32 v20, 0xbfb8aa3b, v20
	v_mul_f32_e32 v18, 0xbfb8aa3b, v18
	v_mul_f32_e32 v22, 0xbfb8aa3b, v22
	v_mul_f32_e32 v23, 0xbfb8aa3b, v23
	v_exp_f32_e32 v20, v20
	v_exp_f32_e32 v18, v18
	v_exp_f32_e32 v22, v22
	v_exp_f32_e32 v23, v23
	v_add_f32_e32 v20, 1.0, v20
	v_add_f32_e32 v18, 1.0, v18
	v_add_f32_e32 v22, 1.0, v22
	v_add_f32_e32 v23, 1.0, v23
	v_rcp_f32_e32 v20, v20
	v_rcp_f32_e32 v21, v18
	v_rcp_f32_e32 v22, v22
	v_rcp_f32_e32 v23, v23
	v_lshlrev_b32_e32 v18, 16, v19
	v_and_b32_e32 v19, 0xffff0000, v19
	v_pk_mul_f32 v[20:21], v[20:21], v[40:41]
	v_pk_mul_f32 v[22:23], v[22:23], v[18:19]
	v_cvt_pk_bf16_f32 v18, v20, v21
	v_cvt_pk_bf16_f32 v19, v22, v23
	global_load_dwordx4 v[20:23], v[174:175], off offset:64
	s_waitcnt vmcnt(0)
	v_add_f32_e32 v20, v24, v20
	v_add_f32_e32 v21, v25, v21
	v_add_f32_e32 v22, v26, v22
	v_add_f32_e32 v23, v27, v23
	v_mul_f32_e32 v20, 0xbfb8aa3b, v20
	v_mul_f32_e32 v21, 0xbfb8aa3b, v21
	v_mul_f32_e32 v22, 0xbfb8aa3b, v22
	v_mul_f32_e32 v23, 0xbfb8aa3b, v23
	v_exp_f32_e32 v20, v20
	v_exp_f32_e32 v21, v21
	v_exp_f32_e32 v22, v22
	v_exp_f32_e32 v23, v23
	v_add_f32_e32 v20, 1.0, v20
	v_add_f32_e32 v21, 1.0, v21
	v_add_f32_e32 v22, 1.0, v22
	v_add_f32_e32 v23, 1.0, v23
	v_rcp_f32_e32 v20, v20
	v_rcp_f32_e32 v21, v21
	v_rcp_f32_e32 v22, v22
	v_rcp_f32_e32 v23, v23
	s_waitcnt vmcnt(0)
	v_mov_b32_e32 v36, v220
	v_mov_b32_e32 v37, v221
	v_lshlrev_b32_e32 v38, 16, v36
	v_and_b32_e32 v39, 0xffff0000, v36
	v_lshlrev_b32_e32 v24, 16, v37
	v_and_b32_e32 v25, 0xffff0000, v37
	v_pk_mul_f32 v[20:21], v[20:21], v[38:39]
	v_pk_mul_f32 v[22:23], v[22:23], v[24:25]
	v_cvt_pk_bf16_f32 v20, v20, v21
	v_cvt_pk_bf16_f32 v21, v22, v23
	global_load_dwordx4 v[22:25], v[174:175], off offset:96
	s_waitcnt vmcnt(0)
	v_add_f32_e32 v22, v28, v22
	v_add_f32_e32 v23, v29, v23
	v_add_f32_e32 v24, v30, v24
	v_add_f32_e32 v25, v31, v25
	v_mul_f32_e32 v22, 0xbfb8aa3b, v22
	v_mul_f32_e32 v23, 0xbfb8aa3b, v23
	v_mul_f32_e32 v24, 0xbfb8aa3b, v24
	v_mul_f32_e32 v25, 0xbfb8aa3b, v25
	v_exp_f32_e32 v22, v22
	v_exp_f32_e32 v23, v23
	v_exp_f32_e32 v24, v24
	v_exp_f32_e32 v25, v25
	v_add_f32_e32 v22, 1.0, v22
	v_add_f32_e32 v23, 1.0, v23
	v_add_f32_e32 v24, 1.0, v24
	v_add_f32_e32 v25, 1.0, v25
	v_rcp_f32_e32 v22, v22
	v_rcp_f32_e32 v23, v23
	v_rcp_f32_e32 v24, v24
	v_rcp_f32_e32 v25, v25
	s_waitcnt vmcnt(0)
	v_mov_b32_e32 v26, v222
	v_mov_b32_e32 v27, v223
	v_lshlrev_b32_e32 v36, 16, v26
	v_and_b32_e32 v37, 0xffff0000, v26
	v_lshlrev_b32_e32 v26, 16, v27
	v_and_b32_e32 v27, 0xffff0000, v27
	v_pk_mul_f32 v[22:23], v[22:23], v[36:37]
	v_pk_mul_f32 v[24:25], v[24:25], v[26:27]
	v_cvt_pk_bf16_f32 v22, v22, v23
	v_cvt_pk_bf16_f32 v23, v24, v25
	v_lshl_add_u64 v[24:25], s[22:23], 0, v[34:35]
	v_lshl_add_u64 v[24:25], v[24:25], 0, s[2:3]
	v_lshl_add_u64 v[24:25], v[24:25], 0, v[188:189]
	v_add_co_u32_e32 v26, vcc, s6, v24
	v_lshl_add_u64 v[28:29], v[24:25], 0, s[14:15]
	s_nop 0
	v_addc_co_u32_e32 v27, vcc, 0, v25, vcc
	global_store_dwordx4 v[26:27], v[16:19], off offset:1536
	global_store_dwordx4 v[28:29], v[20:23], off offset:16
	global_load_dwordx4 v[16:19], v[174:175], off offset:128
	s_nop 0
	s_and_b64 vcc, exec, s[4:5]
	s_waitcnt vmcnt(0)
; DI uint2 pk4(float a, float b, float c, float d) { uint2 r; r.x = pk2(a, b); r.y = pk2(c, d); return r; }
; DI float bflo(unsigned v) { return __uint_as_float(v << 16); }
; DI float bfhi(unsigned v) { return __uint_as_float(v & 0xffff0000u); }
; DI float sigmoidf_(float x) { return __builtin_amdgcn_rcpf(1.f + __builtin_amdgcn_exp2f(-LOG2E * x)); }
;   DI u16* r1() const { return (u16*)(ws + O_R1); }
;   DI u16* ysact() const { return (u16*)(ws + O_YSACT); }
;   DI void operator()(f32x16 (&acc)[2][4], int wm, int wn, int lane) const {
;     ...
;     for (int mt = 0; mt < 4; ++mt) {
;       const int tok = m0 + wm * 128 + mt * 32 + r32;
; #pragma unroll
;       for (int nt = 0; nt < 2; ++nt) {
;         uint2 pk[4];
; #pragma unroll
;         for (int q4 = 0; q4 < 4; ++q4) {
;           const int n = n0 + wn * 64 + nt * 32 + q4 * 8 + hh * 4;
;           const float4 bb = *(const float4*)(gb + n);
;           const uint2 ys = *(const uint2*)(c.ysact() + (size_t)tok * 256 + n);
;           pk[q4] = pk4(bflo(ys.x) * sigmoidf_(acc[nt][mt][q4 * 4 + 0] + bb.x), bfhi(ys.x) * sigmoidf_(acc[nt][mt][q4 * 4 + 1] + bb.y),
;                        bflo(ys.y) * sigmoidf_(acc[nt][mt][q4 * 4 + 2] + bb.z), bfhi(ys.y) * sigmoidf_(acc[nt][mt][q4 * 4 + 3] + bb.w));
;         }
;         u16* d_ = c.r1() + (size_t)tok * 1024 + 768 + n0 + wn * 64 + nt * 32 + hh * 16;
;         *(uint4*)d_ = make_uint4(pk[0].x, pk[0].y, pk[1].x, pk[1].y);
;         *(uint4*)(d_ + 8) = make_uint4(pk[2].x, pk[2].y, pk[3].x, pk[3].y);
;       }
	v_add_f32_e32 v0, v0, v16
	v_add_f32_e32 v1, v1, v17
	v_add_f32_e32 v2, v2, v18
	v_add_f32_e32 v3, v3, v19
	v_mul_f32_e32 v0, 0xbfb8aa3b, v0
	v_mul_f32_e32 v1, 0xbfb8aa3b, v1
	v_mul_f32_e32 v2, 0xbfb8aa3b, v2
	v_mul_f32_e32 v3, 0xbfb8aa3b, v3
	v_exp_f32_e32 v0, v0
	v_exp_f32_e32 v1, v1
	v_exp_f32_e32 v2, v2
	v_exp_f32_e32 v3, v3
	v_add_f32_e32 v0, 1.0, v0
	v_add_f32_e32 v1, 1.0, v1
	v_add_f32_e32 v2, 1.0, v2
	v_add_f32_e32 v3, 1.0, v3
	v_rcp_f32_e32 v0, v0
	v_rcp_f32_e32 v1, v1
	v_rcp_f32_e32 v2, v2
	v_rcp_f32_e32 v3, v3
	s_waitcnt vmcnt(0)
	v_mov_b32_e32 v20, v142
	v_mov_b32_e32 v21, v143
	v_lshlrev_b32_e32 v22, 16, v20
	v_and_b32_e32 v23, 0xffff0000, v20
	v_lshlrev_b32_e32 v16, 16, v21
	v_and_b32_e32 v17, 0xffff0000, v21
	v_pk_mul_f32 v[0:1], v[0:1], v[22:23]
	v_pk_mul_f32 v[2:3], v[2:3], v[16:17]
	v_cvt_pk_bf16_f32 v0, v0, v1
	v_cvt_pk_bf16_f32 v1, v2, v3
	global_load_dwordx4 v[16:19], v[174:175], off offset:160
	s_waitcnt vmcnt(0)
	v_add_f32_e32 v4, v4, v16
	s_waitcnt vmcnt(0)
	v_mov_b32_e32 v2, v144
	v_mov_b32_e32 v3, v145
	v_lshlrev_b32_e32 v20, 16, v2
	v_and_b32_e32 v21, 0xffff0000, v2
	v_add_f32_e32 v2, v5, v17
	v_add_f32_e32 v6, v6, v18
	v_add_f32_e32 v7, v7, v19
	v_mul_f32_e32 v4, 0xbfb8aa3b, v4
	v_mul_f32_e32 v2, 0xbfb8aa3b, v2
	v_mul_f32_e32 v6, 0xbfb8aa3b, v6
	v_mul_f32_e32 v7, 0xbfb8aa3b, v7
	v_exp_f32_e32 v4, v4
	v_exp_f32_e32 v2, v2
	v_exp_f32_e32 v6, v6
	v_exp_f32_e32 v7, v7
	v_add_f32_e32 v4, 1.0, v4
	v_add_f32_e32 v2, 1.0, v2
	v_add_f32_e32 v6, 1.0, v6
	v_add_f32_e32 v7, 1.0, v7
	v_rcp_f32_e32 v4, v4
	v_rcp_f32_e32 v5, v2
	v_rcp_f32_e32 v6, v6
	v_rcp_f32_e32 v7, v7
	v_lshlrev_b32_e32 v2, 16, v3
	v_and_b32_e32 v3, 0xffff0000, v3
	v_pk_mul_f32 v[4:5], v[4:5], v[20:21]
	v_pk_mul_f32 v[6:7], v[6:7], v[2:3]
	v_cvt_pk_bf16_f32 v2, v4, v5
	v_cvt_pk_bf16_f32 v3, v6, v7
	global_load_dwordx4 v[4:7], v[174:175], off offset:192
	s_waitcnt vmcnt(0)
	v_add_f32_e32 v4, v8, v4
	v_add_f32_e32 v5, v9, v5
	v_add_f32_e32 v6, v10, v6
	v_add_f32_e32 v7, v11, v7
	v_mul_f32_e32 v4, 0xbfb8aa3b, v4
	v_mul_f32_e32 v5, 0xbfb8aa3b, v5
	v_mul_f32_e32 v6, 0xbfb8aa3b, v6
	v_mul_f32_e32 v7, 0xbfb8aa3b, v7
	v_exp_f32_e32 v4, v4
	v_exp_f32_e32 v5, v5
	v_exp_f32_e32 v6, v6
	v_exp_f32_e32 v7, v7
	v_add_f32_e32 v4, 1.0, v4
	v_add_f32_e32 v5, 1.0, v5
	v_add_f32_e32 v6, 1.0, v6
	v_add_f32_e32 v7, 1.0, v7
	v_rcp_f32_e32 v4, v4
	v_rcp_f32_e32 v5, v5
	v_rcp_f32_e32 v6, v6
	v_rcp_f32_e32 v7, v7
	s_waitcnt vmcnt(0)
	v_mov_b32_e32 v16, v146
	v_mov_b32_e32 v17, v147
	v_lshlrev_b32_e32 v18, 16, v16
	v_and_b32_e32 v19, 0xffff0000, v16
	v_lshlrev_b32_e32 v8, 16, v17
	v_and_b32_e32 v9, 0xffff0000, v17
	v_pk_mul_f32 v[4:5], v[4:5], v[18:19]
	v_pk_mul_f32 v[6:7], v[6:7], v[8:9]
	v_cvt_pk_bf16_f32 v4, v4, v5
	v_cvt_pk_bf16_f32 v5, v6, v7
	global_load_dwordx4 v[6:9], v[174:175], off offset:224
	s_waitcnt vmcnt(0)
	v_add_f32_e32 v6, v12, v6
	v_add_f32_e32 v7, v13, v7
	v_add_f32_e32 v8, v14, v8
	v_add_f32_e32 v9, v15, v9
	v_mul_f32_e32 v6, 0xbfb8aa3b, v6
	v_mul_f32_e32 v7, 0xbfb8aa3b, v7
	v_mul_f32_e32 v8, 0xbfb8aa3b, v8
	v_mul_f32_e32 v9, 0xbfb8aa3b, v9
	v_exp_f32_e32 v6, v6
	v_exp_f32_e32 v7, v7
	v_exp_f32_e32 v8, v8
	v_exp_f32_e32 v9, v9
	v_add_f32_e32 v6, 1.0, v6
	v_add_f32_e32 v7, 1.0, v7
	v_add_f32_e32 v8, 1.0, v8
	v_add_f32_e32 v9, 1.0, v9
	v_rcp_f32_e32 v6, v6
	v_rcp_f32_e32 v7, v7
	v_rcp_f32_e32 v8, v8
	v_rcp_f32_e32 v9, v9
	s_waitcnt vmcnt(0)
	v_mov_b32_e32 v10, v148
	v_mov_b32_e32 v11, v149
	v_lshlrev_b32_e32 v16, 16, v10
	v_and_b32_e32 v17, 0xffff0000, v10
	v_lshlrev_b32_e32 v10, 16, v11
	v_and_b32_e32 v11, 0xffff0000, v11
	v_pk_mul_f32 v[6:7], v[6:7], v[16:17]
	v_pk_mul_f32 v[8:9], v[8:9], v[10:11]
	v_cvt_pk_bf16_f32 v6, v6, v7
	v_cvt_pk_bf16_f32 v7, v8, v9
	v_lshl_add_u64 v[8:9], v[24:25], 0, s[16:17]
	global_store_dwordx4 v[26:27], v[0:3], off offset:1600
	global_store_dwordx4 v[8:9], v[4:7], off offset:16
	s_cbranch_vccnz .LBB0_360
